# dense: waves 0-3 issue ring DMA at END of matrix phase (under last PV MFMAs); -m straight from v[114:129]; plus P0 rewrite
# baseline (speedup 1.0000x reference)
; #define RESC(a) do { if (__any((a) < 1.f)) { if (hi == 0) al_l[r32] = (a); asm volatile("s_waitcnt lgkmcnt(0)" ::: "memory"); \
;     for (int d = 0; d < 4; ++d) for (int r = 0; r < 16; ++r) o[d][r] *= al_l[crow(r, hi)]; } } while (0)
; #define PSM(P0, P1, MN, AL, jt) do { if constexpr (DIL) { const int t_ = otid(), iq_ = (t_ >> 6) * QBLK + (t_ & 31), hi_ = (t_ >> 5) & 1; \
;       partialSM_dil(P0, P1, m_reg, MN, AL, (float)(-64 - iq_ + 4 * hi_ + 64 * (jt)), fmaxf(-64.f, (float)(-(i0 + iq_))), fminf(64.f, (float)(nsub - 1 - (i0 + iq_))), nslopeC); } \
;     else partialSM(P0, P1, m_reg, MN, AL); } while (0)
; #define PP_BAR_PLAIN() asm volatile("s_waitcnt lgkmcnt(0)\n\ts_barrier" ::: "memory")
; __device__ __forceinline__ void partialSM_neg(f32x16& p0, f32x16& p1, float& m_reg, f32x16& negm, float& alpha, int bounded) {
;   if (bounded) {
;     alpha = 1.f;
; #pragma unroll
;     for (int r = 0; r < 16; ++r) p0[r] = __builtin_amdgcn_exp2f(p0[r]);
;     return;
;   }
;   float pmax = p0[0];
; #pragma unroll
;   for (int r = 1; r < 16; ++r) pmax = fmaxf(pmax, p0[r]);
; #pragma unroll
;   for (int r = 0; r < 16; ++r) pmax = fmaxf(pmax, p1[r]);
;   { auto rr = __builtin_amdgcn_permlane32_swap(__float_as_uint(pmax), __float_as_uint(pmax), false, false);
;     pmax = fmaxf(__uint_as_float(rr[0]), __uint_as_float(rr[1])); }
;   if (__builtin_expect(__all(pmax <= THR), 1)) { alpha = 1.f; }
;   else { const float dl = fmaxf(pmax, 0.f); m_reg += dl; alpha = __builtin_amdgcn_exp2f(-dl);
; #pragma unroll
;     for (int r = 0; r < 16; ++r) { p0[r] -= dl; p1[r] -= dl; negm[r] = -m_reg; } }
; #pragma unroll
;   for (int r = 0; r < 16; ++r) p0[r] = __builtin_amdgcn_exp2f(p0[r]);
; }
;     ...
;       if (grpB && t + 3 < NT) DMA(t + 3, (t + 3) & 3);
;     ...
;       partialSM_neg(pA0, pA1, m_reg, negm, alA, i0); if (!i0) RESC(alA);
;     ...
;       PSM(pA0, pA1, mnA, alA, t); RESC(alA);
;     ...
;       finishSM(pA0, pA1, alA, l_reg, pa0, pa1, pa2, pa3);
;     ...
;       { float dm_ = alA;
; #pragma unroll
;         for (int q_ = 0; q_ < 32; ++q_) asm volatile("v_add_f32 %0, %0, %0" : "+v"(dm_));
;         if (dm_ == 123.456f) l_reg += 1.f; }
;     ...
;       if (!(MK_PREB && t + 1 < NT)) { if (!grpB) PP_BAR(t + 2 < NT); else PP_BAR_PLAIN(); }
;       else if (!grpB) PP_BAR(t + 2 < NT);
;       if (!grpB && t + 3 < NT) DMA(t + 3, (t + 3) & 3);
.LBB0_56:
	v_cndmask_b32_e64 v66, 0, 1, s[82:83]
	v_cmp_ne_u32_e64 s[44:45], 1, v66
	v_lshl_add_u64 v[66:67], v[208:209], 0, s[86:87]
	s_mov_b64 s[40:41], 0xf00c000
	v_lshl_add_u64 v[76:77], v[66:67], 0, s[40:41]
	s_mov_b64 s[40:41], 0xf00c080
	s_andn2_b64 vcc, exec, s[82:83]
	v_lshl_add_u64 v[74:75], v[210:211], 0, s[86:87]
	v_lshl_add_u64 v[78:79], v[212:213], 0, s[86:87]
	v_lshl_add_u64 v[80:81], v[66:67], 0, s[40:41]
	s_cbranch_vccnz .LBB0_58
	s_add_i32 s15, s86, 0xc000
	s_and_b32 s15, s15, 0xc000
	s_add_i32 s40, s13, s15
	s_mov_b32 m0, s40
	s_add_i32 s15, s14, s15
	global_load_lds_dwordx4 v[74:75], off
	s_mov_b32 m0, s15
	s_nop 0
	global_load_lds_dwordx4 v[76:77], off
	s_add_i32 m0, s40, 0x400
	s_nop 0
	global_load_lds_dwordx4 v[78:79], off
	s_add_i32 m0, s15, 0x400
	s_nop 0
	global_load_lds_dwordx4 v[80:81], off
.LBB0_58:
	v_cndmask_b32_e64 v66, 0, 1, s[80:81]
	v_cmp_ne_u32_e64 s[40:41], 1, v66
	s_andn2_b64 vcc, exec, s[80:81]
	v_mov_b32_e32 v242, 1.0
	s_cbranch_vccnz .LBB0_60
	v_max_f32_e32 v66, v99, v99
	v_max_f32_e32 v67, v98, v98
	v_max_f32_e32 v66, v67, v66
	v_max3_f32 v66, v66, v100, v101
	v_max3_f32 v66, v66, v102, v103
	v_max3_f32 v66, v66, v104, v105
	v_max3_f32 v66, v66, v106, v107
	v_max3_f32 v66, v66, v108, v109
	v_max3_f32 v66, v66, v110, v111
	v_max3_f32 v66, v66, v112, v113
	v_max3_f32 v66, v66, v82, v83
	v_max3_f32 v66, v66, v84, v85
	v_max3_f32 v66, v66, v86, v87
	v_max3_f32 v66, v66, v88, v89
	v_max3_f32 v66, v66, v90, v91
	v_max3_f32 v66, v66, v92, v93
	v_max3_f32 v66, v66, v94, v95
	v_max3_f32 v66, v66, v96, v97
	v_mov_b32_e32 v67, v66
	s_nop 1
	v_permlane32_swap_b32_e32 v66, v67
	v_max_f32_e32 v67, v67, v67
	v_max_f32_e32 v66, v66, v66
	v_max_f32_e32 v66, v66, v67
	v_cmp_ge_f32_e32 vcc, s91, v66
	s_cmp_eq_u64 vcc, exec
	v_mov_b32_e32 v242, 1.0
	s_cbranch_scc0 .LBB0_75
.LBB0_60:
	s_and_b64 vcc, exec, s[40:41]
	s_cbranch_vccnz .LBB0_65
.LBB0_61:
	v_cmp_gt_f32_e32 vcc, 1.0, v242
	s_cbranch_vccz .LBB0_65
	s_and_saveexec_b64 s[42:43], s[38:39]
	ds_write_b32 v234, v242 offset:128
	s_or_b64 exec, exec, s[42:43]
	s_waitcnt lgkmcnt(0)
	v_add_u32_e32 v174, s12, v0
	ds_read_b128 v[162:165], v174 offset:224
	ds_read_b128 v[166:169], v174 offset:192
	ds_read_b128 v[170:173], v174 offset:160
	ds_read_b128 v[174:177], v174 offset:128
	s_waitcnt lgkmcnt(0)
	v_pk_mul_f32 v[14:15], v[14:15], v[162:163]
	v_pk_mul_f32 v[10:11], v[10:11], v[166:167]
	v_pk_mul_f32 v[6:7], v[6:7], v[170:171]
	v_pk_mul_f32 v[16:17], v[16:17], v[164:165]
	v_pk_mul_f32 v[12:13], v[12:13], v[168:169]
	v_pk_mul_f32 v[8:9], v[8:9], v[172:173]
	v_pk_mul_f32 v[4:5], v[4:5], v[176:177]
	v_pk_mul_f32 v[2:3], v[2:3], v[174:175]
	v_pk_mul_f32 v[62:63], v[62:63], v[162:163]
	v_pk_mul_f32 v[58:59], v[58:59], v[166:167]
	v_pk_mul_f32 v[54:55], v[54:55], v[170:171]
	v_pk_mul_f32 v[64:65], v[64:65], v[164:165]
	v_pk_mul_f32 v[60:61], v[60:61], v[168:169]
	v_pk_mul_f32 v[56:57], v[56:57], v[172:173]
	v_pk_mul_f32 v[52:53], v[52:53], v[176:177]
	v_pk_mul_f32 v[50:51], v[50:51], v[174:175]
	v_pk_mul_f32 v[46:47], v[46:47], v[162:163]
	v_pk_mul_f32 v[42:43], v[42:43], v[166:167]
	v_pk_mul_f32 v[38:39], v[38:39], v[170:171]
	v_pk_mul_f32 v[48:49], v[48:49], v[164:165]
	v_pk_mul_f32 v[44:45], v[44:45], v[168:169]
	v_pk_mul_f32 v[40:41], v[40:41], v[172:173]
	v_pk_mul_f32 v[36:37], v[36:37], v[176:177]
	v_pk_mul_f32 v[34:35], v[34:35], v[174:175]
	v_pk_mul_f32 v[30:31], v[30:31], v[162:163]
	v_pk_mul_f32 v[26:27], v[26:27], v[166:167]
	v_pk_mul_f32 v[22:23], v[22:23], v[170:171]
	v_pk_mul_f32 v[32:33], v[32:33], v[164:165]
	v_pk_mul_f32 v[28:29], v[28:29], v[168:169]
	v_pk_mul_f32 v[24:25], v[24:25], v[172:173]
	v_pk_mul_f32 v[20:21], v[20:21], v[176:177]
	v_pk_mul_f32 v[18:19], v[18:19], v[174:175]
.LBB0_65:
	v_exp_f32_e32 v98, v98
	v_exp_f32_e32 v99, v99
	v_exp_f32_e32 v100, v100
	v_exp_f32_e32 v101, v101
	v_exp_f32_e32 v102, v102
	v_add_f32_e32 v162, 0, v98
	v_exp_f32_e32 v103, v103
	v_add_f32_e32 v162, v99, v162
	v_exp_f32_e32 v104, v104
	v_add_f32_e32 v162, v100, v162
	v_exp_f32_e32 v105, v105
	v_add_f32_e32 v162, v101, v162
	v_exp_f32_e32 v106, v106
	v_add_f32_e32 v162, v102, v162
	v_exp_f32_e32 v107, v107
	v_add_f32_e32 v162, v103, v162
	v_exp_f32_e32 v108, v108
	v_add_f32_e32 v162, v104, v162
	v_exp_f32_e32 v109, v109
	v_add_f32_e32 v162, v105, v162
	v_exp_f32_e32 v110, v110
	v_add_f32_e32 v162, v106, v162
	v_exp_f32_e32 v111, v111
	v_add_f32_e32 v162, v107, v162
	v_exp_f32_e32 v112, v112
	v_add_f32_e32 v162, v108, v162
	v_exp_f32_e32 v113, v113
	v_add_f32_e32 v162, v109, v162
	v_exp_f32_e32 v82, v82
	v_add_f32_e32 v162, v110, v162
	v_exp_f32_e32 v83, v83
	v_add_f32_e32 v162, v111, v162
	v_exp_f32_e32 v84, v84
	v_add_f32_e32 v162, v112, v162
	v_exp_f32_e32 v85, v85
	v_add_f32_e32 v162, v113, v162
	v_exp_f32_e32 v86, v86
	v_add_f32_e32 v162, v82, v162
	v_exp_f32_e32 v87, v87
	v_add_f32_e32 v162, v83, v162
	v_exp_f32_e32 v88, v88
	v_add_f32_e32 v162, v84, v162
	v_exp_f32_e32 v89, v89
	v_add_f32_e32 v162, v85, v162
	v_exp_f32_e32 v90, v90
	v_add_f32_e32 v162, v86, v162
	v_exp_f32_e32 v91, v91
	v_add_f32_e32 v162, v87, v162
	v_exp_f32_e32 v92, v92
	v_add_f32_e32 v162, v88, v162
	v_exp_f32_e32 v93, v93
	v_add_f32_e32 v162, v89, v162
	v_exp_f32_e32 v94, v94
	v_add_f32_e32 v162, v90, v162
	v_exp_f32_e32 v95, v95
	v_add_f32_e32 v162, v91, v162
	v_exp_f32_e32 v96, v96
	v_add_f32_e32 v162, v92, v162
	v_exp_f32_e32 v97, v97
	v_add_f32_e32 v162, v93, v162
	v_add_f32_e32 v162, v94, v162
	v_add_f32_e32 v162, v95, v162
	v_add_f32_e32 v162, v96, v162
	v_add_f32_e32 v243, v97, v162
	v_mov_b32_e32 v245, v243
	v_cvt_pk_bf16_f32 v166, v82, v83
	v_cndmask_b32_e64 v82, 0, 1, s[0:1]
	s_nop 0
	v_permlane32_swap_b32_e32 v243, v245
	v_cmp_ne_u32_e64 s[42:43], 1, v82
	s_andn2_b64 vcc, exec, s[0:1]
	v_cvt_pk_bf16_f32 v174, v98, v99
	v_cvt_pk_bf16_f32 v175, v100, v101
	v_cvt_pk_bf16_f32 v176, v102, v103
	v_cvt_pk_bf16_f32 v177, v104, v105
	v_cvt_pk_bf16_f32 v170, v106, v107
	v_cvt_pk_bf16_f32 v171, v108, v109
	v_cvt_pk_bf16_f32 v172, v110, v111
	v_cvt_pk_bf16_f32 v173, v112, v113
	v_cvt_pk_bf16_f32 v167, v84, v85
	v_cvt_pk_bf16_f32 v168, v86, v87
	v_cvt_pk_bf16_f32 v169, v88, v89
	v_cvt_pk_bf16_f32 v162, v90, v91
	v_cvt_pk_bf16_f32 v163, v92, v93
	v_cvt_pk_bf16_f32 v164, v94, v95
	v_cvt_pk_bf16_f32 v165, v96, v97
	s_cbranch_vccnz .LBB0_67
	s_waitcnt vmcnt(4) lgkmcnt(0)
	s_barrier

; #define SBAR() __builtin_amdgcn_sched_barrier(0)
; #define KRD(f, d0, kb) asm volatile("ds_read_b128 %0, %2 offset:%3\n\tds_read_b128 %1, %2 offset:%4" : "=&v"(f.a), "=&v"(f.b) : "v"((kb) + koff[(d0) & 3]), "i"(((d0) >> 2) * 128), "i"(((d0) >> 2) * 128 + 8192) : "memory")
; #define QMM(f, d0) do { pA0 = __builtin_amdgcn_mfma_f32_32x32x16_bf16(f.a, qr[d0], pA0, 0, 0, 0); pA1 = __builtin_amdgcn_mfma_f32_32x32x16_bf16(f.b, qr[d0], pA1, 0, 0, 0); } while (0)
; #define LW(n) do { asm volatile("s_waitcnt lgkmcnt(" #n ")" ::: "memory"); SBAR(); } while (0)
; #define PP_BAR(VM) do { if (VM) { asm volatile("s_waitcnt vmcnt(4) lgkmcnt(0)\n\ts_barrier" ::: "memory"); } else { asm volatile("s_waitcnt vmcnt(0) lgkmcnt(0)\n\ts_barrier" ::: "memory"); } } while (0)
; #define PP_BAR_PLAIN() asm volatile("s_waitcnt lgkmcnt(0)\n\ts_barrier" ::: "memory")
;     ...
;       if (t + 1 < NT) {
;         const int kb_ = kbase0 + ((t + 1) & 3) * (int)SHM_K, vb_ = VBUF(t);
;         KFrag k0_, k1_; VFrag fa_, fb_;
;         KRD(k0_, 0, kb_); KRD(k1_, 1, kb_); pv_rd<0>(fa_, vb_);
;         if (MK_PREB && grpB) asm volatile("s_barrier" ::: "memory");
;     ...
;         LW(10); pA0 = __builtin_amdgcn_mfma_f32_32x32x16_bf16(k0_.a, qr[0], negm, 0, 0, 0); pA1 = __builtin_amdgcn_mfma_f32_32x32x16_bf16(k0_.b, qr[0], negm, 0, 0, 0); SBAR(); KRD(k0_, 2, kb_);
;     ...
;         pA0 = f32x16{}; pA1 = f32x16{};
;         LW(10); QMM(k0_, 0); SBAR(); KRD(k0_, 2, kb_);
;     ...
;         LW(10); QMM(k1_, 1); SBAR(); KRD(k1_, 3, kb_);
;         LW(4);  pv_mm(o[0], fa_, pa0, pa1, pa2, pa3); SBAR(); pv_rd<1>(fb_, vb_);
;         LW(10); QMM(k0_, 2); SBAR(); KRD(k0_, 4, kb_);
;         LW(10); QMM(k1_, 3); SBAR(); KRD(k1_, 5, kb_);
;         LW(4);  pv_mm(o[1], fb_, pa0, pa1, pa2, pa3); SBAR(); pv_rd<2>(fa_, vb_);
;         LW(10); QMM(k0_, 4); SBAR(); KRD(k0_, 6, kb_);
;         LW(10); QMM(k1_, 5); SBAR(); KRD(k1_, 7, kb_);
;         LW(4);  pv_mm(o[2], fa_, pa0, pa1, pa2, pa3); SBAR(); pv_rd<3>(fb_, vb_);
;         LW(10); QMM(k0_, 6); SBAR();
;         LW(8);  QMM(k1_, 7); SBAR();
;         LW(0);  pv_mm(o[3], fb_, pa0, pa1, pa2, pa3);
;       } else pv_d0(o, VBUF(t), pa0, pa1, pa2, pa3);
;       if (t + 1 < NT) { if (grpB) PP_BAR(t + 3 < NT); else PP_BAR_PLAIN(); }
.LBB0_69:
	s_waitcnt lgkmcnt(10)
	v_mfma_f32_32x32x16_bf16 v[98:113], v[82:85], v[158:161], v[114:129]
	v_mfma_f32_32x32x16_bf16 v[82:97], v[202:205], v[158:161], v[114:129]
	v_add_u32_e32 v217, s87, v237
	ds_read_b128 v[202:205], v217 offset:0
	ds_read_b128 v[250:253], v217 offset:0x2000
	s_waitcnt lgkmcnt(10)
	v_mfma_f32_32x32x16_bf16 v[98:113], v[198:201], v[154:157], v[98:113]
	v_mfma_f32_32x32x16_bf16 v[82:97], v[194:197], v[154:157], v[82:97]
	v_add_u32_e32 v206, s87, v236
	ds_read_b128 v[194:197], v206 offset:0
	ds_read_b128 v[198:201], v206 offset:0x2000
	s_waitcnt lgkmcnt(4)
	v_mfma_f32_32x32x16_bf16 v[2:17], v[174:177], v[190:193], v[2:17]
	ds_read_b64_tr_b16 v[190:191], v246 offset:0x3200
	ds_read_b64_tr_b16 v[192:193], v246 offset:0x3a00
	v_mfma_f32_32x32x16_bf16 v[2:17], v[170:173], v[186:189], v[2:17]
	ds_read_b64_tr_b16 v[186:187], v246 offset:0x2200
	ds_read_b64_tr_b16 v[188:189], v246 offset:0x2a00
	v_mfma_f32_32x32x16_bf16 v[2:17], v[166:169], v[182:185], v[2:17]
	ds_read_b64_tr_b16 v[182:183], v246 offset:0x1200
	ds_read_b64_tr_b16 v[184:185], v246 offset:0x1a00
	v_mfma_f32_32x32x16_bf16 v[2:17], v[162:165], v[178:181], v[2:17]
	ds_read_b64_tr_b16 v[178:179], v246 offset:0x200
	ds_read_b64_tr_b16 v[180:181], v246 offset:0xa00
	s_waitcnt lgkmcnt(10)
	v_mfma_f32_32x32x16_bf16 v[98:113], v[202:205], v[150:153], v[98:113]
	v_mfma_f32_32x32x16_bf16 v[82:97], v[250:253], v[150:153], v[82:97]
	ds_read_b128 v[202:205], v248 offset:0x80
	ds_read_b128 v[250:253], v248 offset:0x2080
	s_waitcnt lgkmcnt(10)
	v_mfma_f32_32x32x16_bf16 v[98:113], v[194:197], v[146:149], v[98:113]
	v_mfma_f32_32x32x16_bf16 v[82:97], v[198:201], v[146:149], v[82:97]
	ds_read_b128 v[194:197], v247 offset:0x80
	ds_read_b128 v[198:201], v247 offset:0x2080
	s_waitcnt lgkmcnt(4)
	v_mfma_f32_32x32x16_bf16 v[50:65], v[174:177], v[178:181], v[50:65]
	ds_read_b64_tr_b16 v[178:179], v246 offset:0x400
	ds_read_b64_tr_b16 v[180:181], v246 offset:0xc00
	v_mfma_f32_32x32x16_bf16 v[50:65], v[170:173], v[182:185], v[50:65]
	ds_read_b64_tr_b16 v[182:183], v246 offset:0x1400
	ds_read_b64_tr_b16 v[184:185], v246 offset:0x1c00
	v_mfma_f32_32x32x16_bf16 v[50:65], v[166:169], v[186:189], v[50:65]
	ds_read_b64_tr_b16 v[186:187], v246 offset:0x2400
	ds_read_b64_tr_b16 v[188:189], v246 offset:0x2c00
	v_mfma_f32_32x32x16_bf16 v[50:65], v[162:165], v[190:193], v[50:65]
	ds_read_b64_tr_b16 v[190:191], v246 offset:0x3400
	ds_read_b64_tr_b16 v[192:193], v246 offset:0x3c00
	s_waitcnt lgkmcnt(10)
	v_mfma_f32_32x32x16_bf16 v[98:113], v[202:205], v[142:145], v[98:113]
	v_mfma_f32_32x32x16_bf16 v[82:97], v[250:253], v[142:145], v[82:97]
	ds_read_b128 v[202:205], v217 offset:0x80
	ds_read_b128 v[248:251], v217 offset:0x2080
	s_waitcnt lgkmcnt(10)
	v_mfma_f32_32x32x16_bf16 v[98:113], v[194:197], v[138:141], v[98:113]
	v_mfma_f32_32x32x16_bf16 v[82:97], v[198:201], v[138:141], v[82:97]
	ds_read_b128 v[194:197], v206 offset:0x80
	ds_read_b128 v[198:201], v206 offset:0x2080
	s_waitcnt lgkmcnt(4)
	v_mfma_f32_32x32x16_bf16 v[34:49], v[174:177], v[178:181], v[34:49]
	ds_read_b64_tr_b16 v[178:179], v246 offset:0x600
	ds_read_b64_tr_b16 v[180:181], v246 offset:0xe00
	v_mfma_f32_32x32x16_bf16 v[34:49], v[170:173], v[182:185], v[34:49]
	ds_read_b64_tr_b16 v[182:183], v246 offset:0x1600
	ds_read_b64_tr_b16 v[184:185], v246 offset:0x1e00
	v_mfma_f32_32x32x16_bf16 v[34:49], v[166:169], v[186:189], v[34:49]
	ds_read_b64_tr_b16 v[186:187], v246 offset:0x2600
	ds_read_b64_tr_b16 v[188:189], v246 offset:0x2e00
	v_mfma_f32_32x32x16_bf16 v[34:49], v[162:165], v[190:193], v[34:49]
	ds_read_b64_tr_b16 v[190:191], v246 offset:0x3600
	ds_read_b64_tr_b16 v[192:193], v246 offset:0x3e00
	s_waitcnt lgkmcnt(10)
	v_mfma_f32_32x32x16_bf16 v[98:113], v[202:205], v[134:137], v[98:113]
	v_mfma_f32_32x32x16_bf16 v[82:97], v[248:251], v[134:137], v[82:97]
	s_waitcnt lgkmcnt(8)
	v_mfma_f32_32x32x16_bf16 v[98:113], v[194:197], v[130:133], v[98:113]
	v_mfma_f32_32x32x16_bf16 v[82:97], v[198:201], v[130:133], v[82:97]
	s_waitcnt lgkmcnt(0)
	v_mfma_f32_32x32x16_bf16 v[18:33], v[174:177], v[178:181], v[18:33]
	s_mov_b64 s[86:87], -1
	s_and_b64 vcc, exec, s[0:1]
	v_mfma_f32_32x32x16_bf16 v[18:33], v[170:173], v[182:185], v[18:33]
	v_mfma_f32_32x32x16_bf16 v[18:33], v[166:169], v[186:189], v[18:33]
	v_mfma_f32_32x32x16_bf16 v[18:33], v[162:165], v[190:193], v[18:33]
	s_cbranch_vccz .LBB0_72
	s_add_i32 vcc_lo, s84, 0x8000
	s_and_b32 vcc_lo, vcc_lo, 0xc000
	s_add_i32 vcc_hi, s14, vcc_lo
	s_add_i32 vcc_lo, s13, vcc_lo
	s_mov_b32 m0, vcc_lo
	s_nop 0
	global_load_lds_dwordx4 v[74:75], off
	s_mov_b32 m0, vcc_hi
	s_nop 0
	global_load_lds_dwordx4 v[76:77], off
	s_add_i32 m0, vcc_lo, 0x400
	s_nop 0
	global_load_lds_dwordx4 v[78:79], off
	s_add_i32 m0, vcc_hi, 0x400
	s_nop 0
	global_load_lds_dwordx4 v[80:81], off
	s_waitcnt lgkmcnt(0)
	s_barrier
	s_cbranch_execz .LBB0_73

; __device__ __forceinline__ void partialSM_neg(f32x16& p0, f32x16& p1, float& m_reg, f32x16& negm, float& alpha, int bounded) {
;   if (bounded) {
;     alpha = 1.f;
; #pragma unroll
;     for (int r = 0; r < 16; ++r) p0[r] = __builtin_amdgcn_exp2f(p0[r]);
;     return;
;   }
;   float pmax = p0[0];
; #pragma unroll
;   for (int r = 1; r < 16; ++r) pmax = fmaxf(pmax, p0[r]);
; #pragma unroll
;   for (int r = 0; r < 16; ++r) pmax = fmaxf(pmax, p1[r]);
;   { auto rr = __builtin_amdgcn_permlane32_swap(__float_as_uint(pmax), __float_as_uint(pmax), false, false);
;     pmax = fmaxf(__uint_as_float(rr[0]), __uint_as_float(rr[1])); }
;   if (__builtin_expect(__all(pmax <= THR), 1)) { alpha = 1.f; }
;   else { const float dl = fmaxf(pmax, 0.f); m_reg += dl; alpha = __builtin_amdgcn_exp2f(-dl);
; #pragma unroll
;     for (int r = 0; r < 16; ++r) { p0[r] -= dl; p1[r] -= dl; negm[r] = -m_reg; } }
; #pragma unroll
;   for (int r = 0; r < 16; ++r) p0[r] = __builtin_amdgcn_exp2f(p0[r]);
; }
.LBB0_75:
	v_max_f32_e32 v66, v66, v66
	v_max_f32_e32 v67, 0, v66
	v_exp_f32_e64 v242, -v67
	v_add_f32_e32 v240, v240, v67
	v_xor_b32_e32 v66, 0x80000000, v240
	v_sub_f32_e32 v113, v113, v67
	v_sub_f32_e32 v112, v112, v67
	v_sub_f32_e32 v111, v111, v67
	v_sub_f32_e32 v110, v110, v67
	v_sub_f32_e32 v109, v109, v67
	v_sub_f32_e32 v108, v108, v67
	v_sub_f32_e32 v107, v107, v67
	v_sub_f32_e32 v106, v106, v67
	v_sub_f32_e32 v105, v105, v67
	v_sub_f32_e32 v104, v104, v67
	v_sub_f32_e32 v103, v103, v67
	v_sub_f32_e32 v102, v102, v67
	v_sub_f32_e32 v101, v101, v67
	v_sub_f32_e32 v100, v100, v67
	v_sub_f32_e32 v99, v99, v67
	v_sub_f32_e32 v98, v98, v67
	v_sub_f32_e32 v97, v97, v67
	v_sub_f32_e32 v96, v96, v67
	v_sub_f32_e32 v95, v95, v67
	v_sub_f32_e32 v94, v94, v67
	v_sub_f32_e32 v93, v93, v67
	v_sub_f32_e32 v92, v92, v67
	v_sub_f32_e32 v91, v91, v67
	v_sub_f32_e32 v90, v90, v67
	v_sub_f32_e32 v89, v89, v67
	v_sub_f32_e32 v88, v88, v67
	v_sub_f32_e32 v87, v87, v67
	v_sub_f32_e32 v86, v86, v67
	v_sub_f32_e32 v85, v85, v67
	v_sub_f32_e32 v84, v84, v67
	v_sub_f32_e32 v83, v83, v67
	v_sub_f32_e32 v82, v82, v67
	v_mov_b32_e32 v67, v66
	v_mov_b32_e32 v129, v66
	v_mov_b32_e32 v128, v66
	v_mov_b32_e32 v127, v66
	v_mov_b32_e32 v126, v66
	v_mov_b32_e32 v125, v66
	v_mov_b32_e32 v124, v66
	v_mov_b32_e32 v123, v66
	v_mov_b32_e32 v122, v66
	v_mov_b32_e32 v121, v66
	v_mov_b32_e32 v120, v66
	v_mov_b32_e32 v119, v66
	v_mov_b32_e32 v118, v66
	v_mov_b32_e32 v117, v66
	v_mov_b32_e32 v116, v66
	v_mov_b32_e32 v115, v66
	v_mov_b32_e32 v114, v66
	s_and_b64 vcc, exec, s[40:41]
	s_cbranch_vccz .LBB0_61
	s_branch .LBB0_65
.LBB0_76:
	v_mov_b64_e32 v[66:67], v[114:115]
	v_mov_b64_e32 v[68:69], v[116:117]
	v_mov_b64_e32 v[70:71], v[118:119]
	v_mov_b64_e32 v[72:73], v[120:121]
	v_mov_b64_e32 v[74:75], v[122:123]
	v_mov_b64_e32 v[76:77], v[124:125]
	v_mov_b64_e32 v[78:79], v[126:127]
	v_mov_b64_e32 v[80:81], v[128:129]
	s_and_b64 vcc, exec, s[40:41]
	v_mov_b32_e32 v191, 1.0
	s_cbranch_vccnz .LBB0_78
	v_max_f32_e32 v114, v99, v99
	v_max_f32_e32 v115, v98, v98
	v_max_f32_e32 v114, v115, v114
	v_max3_f32 v114, v114, v100, v101
	v_max3_f32 v114, v114, v102, v103
	v_max3_f32 v114, v114, v104, v105
	v_max3_f32 v114, v114, v106, v107
	v_max3_f32 v114, v114, v108, v109
	v_max3_f32 v114, v114, v110, v111
	v_max3_f32 v114, v114, v112, v113
	v_max3_f32 v114, v114, v82, v83
	v_max3_f32 v114, v114, v84, v85
	v_max3_f32 v114, v114, v86, v87
	v_max3_f32 v114, v114, v88, v89
	v_max3_f32 v114, v114, v90, v91
	v_max3_f32 v114, v114, v92, v93
	v_max3_f32 v114, v114, v94, v95
	v_max3_f32 v114, v114, v96, v97
	v_mov_b32_e32 v115, v114
	s_nop 1
	v_permlane32_swap_b32_e32 v114, v115
	v_max_f32_e32 v115, v115, v115
	v_max_f32_e32 v114, v114, v114
	v_max_f32_e32 v114, v114, v115
	v_cmp_ge_f32_e32 vcc, s91, v114
	s_cmp_eq_u64 vcc, exec
	v_mov_b32_e32 v191, 1.0
	s_cbranch_scc0 .LBB0_121
